# combo19 + P3: second indexer unit's query/weight loads issued at the start of the first unit's top-k into registers the top-k never touches, copied into place at the unit head
# speedup vs baseline: 1.0079x; 1.0079x over previous
.Lidx_skipq2:
	s_cmp_eq_u32 s32, 2
	s_cbranch_scc0 .Lq2_nocopy
	s_waitcnt vmcnt(0)
	v_mov_b32_e32 v96, v180
	v_mov_b32_e32 v97, v181
	v_mov_b32_e32 v98, v182
	v_mov_b32_e32 v99, v183
	v_mov_b32_e32 v100, v184
	v_mov_b32_e32 v101, v185
	v_mov_b32_e32 v102, v186
	v_mov_b32_e32 v103, v187
	v_mov_b32_e32 v104, v188
	v_mov_b32_e32 v105, v189
	v_mov_b32_e32 v106, v190
	v_mov_b32_e32 v107, v191
	v_mov_b32_e32 v108, v192
	v_mov_b32_e32 v109, v193
	v_mov_b32_e32 v110, v194
	v_mov_b32_e32 v111, v195
	v_mov_b32_e32 v112, v196
	v_mov_b32_e32 v113, v197
	v_mov_b32_e32 v114, v198
	v_mov_b32_e32 v115, v199
	v_mov_b32_e32 v116, v200
	v_mov_b32_e32 v117, v201
	v_mov_b32_e32 v118, v202
	v_mov_b32_e32 v119, v203
	v_mov_b32_e32 v120, v204
	v_mov_b32_e32 v121, v205
	v_mov_b32_e32 v122, v206
	v_mov_b32_e32 v123, v207
	v_mov_b32_e32 v124, v236
	v_mov_b32_e32 v125, v237
	v_mov_b32_e32 v126, v238
	v_mov_b32_e32 v127, v239
	v_mov_b32_e32 v128, v32
	v_mov_b32_e32 v129, v33
	v_mov_b32_e32 v130, v34
	v_mov_b32_e32 v131, v35
	v_mov_b32_e32 v132, v36
	v_mov_b32_e32 v133, v37
	v_mov_b32_e32 v134, v38
	v_mov_b32_e32 v135, v39
	v_mov_b32_e32 v136, v40
	v_mov_b32_e32 v137, v41
	v_mov_b32_e32 v138, v42
	v_mov_b32_e32 v139, v43
	v_mov_b32_e32 v140, v44
	v_mov_b32_e32 v141, v45
	v_mov_b32_e32 v142, v46
	v_mov_b32_e32 v143, v47
	v_mov_b32_e32 v144, v48
	v_mov_b32_e32 v145, v49
	v_mov_b32_e32 v146, v50
	v_mov_b32_e32 v147, v51
	v_mov_b32_e32 v148, v52
	v_mov_b32_e32 v149, v53
	v_mov_b32_e32 v150, v54
	v_mov_b32_e32 v151, v55
	v_mov_b32_e32 v152, v56
	v_mov_b32_e32 v153, v57
	v_mov_b32_e32 v154, v58
	v_mov_b32_e32 v155, v59
	v_mov_b32_e32 v156, v60
	v_mov_b32_e32 v157, v61
	v_mov_b32_e32 v158, v62
	v_mov_b32_e32 v159, v63
	v_mov_b32_e32 v160, v64
	v_mov_b32_e32 v161, v65
	v_mov_b32_e32 v162, v66
	v_mov_b32_e32 v163, v67
	v_mov_b32_e32 v164, v68
	v_mov_b32_e32 v165, v69
	v_mov_b32_e32 v166, v70
	v_mov_b32_e32 v167, v71
	v_mov_b32_e32 v168, v72
	v_mov_b32_e32 v169, v73
	v_mov_b32_e32 v170, v74
	v_mov_b32_e32 v171, v75
	v_mov_b32_e32 v172, v76
	v_mov_b32_e32 v173, v77
	v_mov_b32_e32 v174, v78
	v_mov_b32_e32 v175, v79
	v_mov_b32_e32 v176, v80
	v_mov_b32_e32 v177, v81
	v_mov_b32_e32 v178, v82
	v_mov_b32_e32 v179, v83
	v_mov_b32_e32 v180, v84
	v_mov_b32_e32 v181, v85
	v_mov_b32_e32 v182, v86
	v_mov_b32_e32 v183, v87
	v_mov_b32_e32 v184, v88
	v_mov_b32_e32 v185, v89
	v_mov_b32_e32 v186, v90
	v_mov_b32_e32 v187, v91
	v_mov_b32_e32 v188, v92
	v_mov_b32_e32 v189, v93
	v_mov_b32_e32 v190, v94
	v_mov_b32_e32 v191, v95

.Lidxt3_join:
.LBB0_1181:
	s_add_i32 s21, s67, s74
	s_cmpk_gt_i32 s21, 0x1ff
	s_cbranch_scc1 .Lq2_skip
	s_lshr_b32 s22, s21, 6
	s_and_b32 s22, s22, 2
	s_ashr_i32 s23, s21, 8
	s_add_i32 s22, s22, s23
	s_and_b32 s23, s21, 0x7f
	s_xor_b32 s24, s23, 0x7f
	s_cmpk_lt_u32 s21, 0x100
	s_cselect_b32 s23, s23, s24
	s_lshl_b32 s23, s23, 4
	s_add_i32 s23, s23, s35
	s_lshl_b32 s24, s22, 11
	s_add_i32 s24, s24, s23
	s_mov_b32 s25, 0
	s_lshl_b64 s[26:27], s[24:25], 13
	s_add_u32 s26, s18, s26
	s_addc_u32 s27, s19, s27
	s_mov_b64 s[28:29], 0x2000
	v_lshlrev_b32_e32 v240, 7, v209
	v_mov_b32_e32 v241, 0
	v_lshlrev_b32_e32 v242, 3, v223
	v_mov_b32_e32 v243, 0
	v_lshl_add_u64 v[240:241], v[240:241], 1, s[26:27]
	v_lshl_add_u64 v[240:241], v[242:243], 1, v[240:241]
	v_lshl_add_u64 v[242:243], v[240:241], 0, s[28:29]
	global_load_dwordx4 v[32:35], v[240:241], off
	global_load_dwordx4 v[36:39], v[240:241], off offset:32
	global_load_dwordx4 v[40:43], v[242:243], off
	global_load_dwordx4 v[44:47], v[242:243], off offset:32
	global_load_dwordx4 v[48:51], v[240:241], off offset:64
	global_load_dwordx4 v[52:55], v[240:241], off offset:96
	global_load_dwordx4 v[56:59], v[242:243], off offset:64
	global_load_dwordx4 v[60:63], v[242:243], off offset:96
	global_load_dwordx4 v[64:67], v[240:241], off offset:128
	global_load_dwordx4 v[68:71], v[240:241], off offset:160
	global_load_dwordx4 v[72:75], v[242:243], off offset:128
	global_load_dwordx4 v[76:79], v[242:243], off offset:160
	global_load_dwordx4 v[80:83], v[240:241], off offset:192
	global_load_dwordx4 v[84:87], v[240:241], off offset:224
	global_load_dwordx4 v[88:91], v[242:243], off offset:192
	global_load_dwordx4 v[92:95], v[242:243], off offset:224
	s_lshl_b64 s[26:27], s[24:25], 7
	s_add_u32 s26, s80, s26
	s_addc_u32 s27, s81, s27
	v_lshlrev_b32_e32 v240, 2, v223
	v_mov_b32_e32 v241, 0
	v_lshl_add_u64 v[240:241], v[240:241], 2, s[26:27]
	global_load_dwordx4 v[236:239], v[240:241], off
	global_load_dwordx4 v[200:203], v[240:241], off offset:32
	global_load_dwordx4 v[204:207], v[240:241], off offset:128
	global_load_dwordx4 v[196:199], v[240:241], off offset:160
	global_load_dwordx4 v[192:195], v[240:241], off offset:64
	global_load_dwordx4 v[184:187], v[240:241], off offset:96
	global_load_dwordx4 v[188:191], v[240:241], off offset:192
	global_load_dwordx4 v[180:183], v[240:241], off offset:224
	s_mov_b32 s32, 2
